# branch-sum phase: next row's six gate-product loads prefetched while the current row is summed (counted vmcnt), global stores
# baseline (speedup 1.0000x reference)
; DI unsigned pk_bf16(float lo, float hi) { unsigned r; asm("v_cvt_pk_bf16_f32 %0, %1, %2" : "=v"(r) : "v"(lo), "v"(hi)); return r; }
; DI float lo_f(unsigned w) { return __uint_as_float(w << 16); }
; DI float hi_f(unsigned w) { return __uint_as_float(w & 0xffff0000u); }
; DI int obid() { int t = blockIdx.x; asm volatile("" : "+s"(t)); return t; }
; DI int ogrid() { int t = gridDim.x; asm volatile("" : "+s"(t)); return t; }
; DI int otid() { int t = threadIdx.x; asm volatile("" : "+v"(t)); return t; }
; DI void phase_merge_sum(const bf16_t* P, bf16_t* M2, int nrows) {
;     const int lane = otid() & 63, wave = otid() >> 6;
;     for (int r = obid() * 8 + wave; r < nrows; r += ogrid() * 8) {
;         const bf16_t* gp = P + (size_t)r * IN_DIM + C_MG + lane * 8;
;         u32x4 v[3][2];
; #pragma unroll
;         for (int b = 0; b < 3; ++b)
; #pragma unroll
;             for (int i = 0; i < 2; ++i) v[b][i] = __builtin_nontemporal_load((const u32x4*)(gp + b * 1024 + i * 512));
; #pragma unroll
;         for (int i = 0; i < 2; ++i) {
;             u32x4 o;
; #pragma unroll
;             for (int j = 0; j < 4; ++j) o[j] = pk_bf16(lo_f(v[0][i][j]) + lo_f(v[1][i][j]) + lo_f(v[2][i][j]), hi_f(v[0][i][j]) + hi_f(v[1][i][j]) + hi_f(v[2][i][j]));
;             *(u32x4*)(M2 + (size_t)r * 1024 + i * 512 + lane * 8) = o;
;         }
;     }
; }
.LBB0_115:
	s_and_b64 vcc, exec, s[14:15]
	s_cbranch_vccz .LBB0_121
	s_cmp_eq_u32 s31, 5
	s_mov_b64 s[4:5], -1
	s_cbranch_scc0 .LBB0_121
	v_mov_b32_e32 v0, v176
	v_mov_b32_e32 v2, v176
	s_mov_b32 s2, s33
	v_ashrrev_i32_e32 v2, 6, v2
	s_nop 0
	v_lshl_add_u32 v2, s2, 3, v2
	v_cmp_gt_i32_e32 vcc, s9, v2
	s_and_saveexec_b64 s[14:15], vcc
	s_cbranch_execz .LBB0_120
	v_lshlrev_b32_e32 v0, 4, v0
	v_and_b32_e32 v0, 0x3f0, v0
	v_lshl_add_u64 v[4:5], s[34:35], 0, v[0:1]
	v_lshl_add_u64 v[6:7], s[76:77], 0, v[0:1]
	s_mov_b64 s[16:17], 0
	v_mad_i64_i32 v[90:91], s[2:3], v2, s28, v[6:7]
	s_mov_b64 s[2:3], 0x1000
	v_lshl_add_u64 v[92:93], v[90:91], 0, s[2:3]
	global_load_dwordx4 v[64:67], v[90:91], off offset:3648 nt
	global_load_dwordx4 v[68:71], v[92:93], off offset:1600 nt
	global_load_dwordx4 v[72:75], v[92:93], off offset:576 nt
	global_load_dwordx4 v[76:79], v[92:93], off offset:2624 nt
	global_load_dwordx4 v[80:83], v[92:93], off offset:3648 nt
	v_lshl_add_u64 v[92:93], v[92:93], 0, s[2:3]
	global_load_dwordx4 v[84:87], v[92:93], off offset:576 nt
	s_waitcnt vmcnt(0)
.LBB0_119:
	s_waitcnt vmcnt(2)
	v_mov_b32_e32 v8, v64
	v_mov_b32_e32 v9, v65
	v_mov_b32_e32 v10, v66
	v_mov_b32_e32 v11, v67
	v_mov_b32_e32 v12, v68
	v_mov_b32_e32 v13, v69
	v_mov_b32_e32 v14, v70
	v_mov_b32_e32 v15, v71
	v_mov_b32_e32 v16, v72
	v_mov_b32_e32 v17, v73
	v_mov_b32_e32 v18, v74
	v_mov_b32_e32 v19, v75
	v_mov_b32_e32 v20, v76
	v_mov_b32_e32 v21, v77
	v_mov_b32_e32 v22, v78
	v_mov_b32_e32 v23, v79
	v_mov_b32_e32 v24, v80
	v_mov_b32_e32 v25, v81
	v_mov_b32_e32 v26, v82
	v_mov_b32_e32 v27, v83
	v_mov_b32_e32 v28, v84
	v_mov_b32_e32 v29, v85
	v_mov_b32_e32 v30, v86
	v_mov_b32_e32 v31, v87
	v_lshl_add_u32 v88, s66, 3, v2
	s_add_i32 s3, s9, -1
	v_min_i32_e32 v88, s3, v88
	v_mad_i64_i32 v[90:91], s[2:3], v88, s28, v[6:7]
	s_mov_b64 s[2:3], 0x1000
	v_lshl_add_u64 v[92:93], v[90:91], 0, s[2:3]
	global_load_dwordx4 v[64:67], v[90:91], off offset:3648 nt
	global_load_dwordx4 v[68:71], v[92:93], off offset:1600 nt
	global_load_dwordx4 v[72:75], v[92:93], off offset:576 nt
	global_load_dwordx4 v[76:79], v[92:93], off offset:2624 nt
	global_load_dwordx4 v[80:83], v[92:93], off offset:3648 nt
	v_lshl_add_u64 v[92:93], v[92:93], 0, s[2:3]
	global_load_dwordx4 v[84:87], v[92:93], off offset:576 nt
	v_ashrrev_i32_e32 v3, 31, v2
	v_lshlrev_b64 v[32:33], 11, v[2:3]
	v_lshl_add_u64 v[32:33], v[4:5], 0, v[32:33]
	s_mov_b32 s2, s66
	v_lshlrev_b32_e32 v0, 16, v8
	v_lshlrev_b32_e32 v35, 16, v11
	v_and_b32_e32 v11, 0xffff0000, v11
	v_lshlrev_b32_e32 v36, 16, v12
	v_lshlrev_b32_e32 v39, 16, v15
	v_and_b32_e32 v15, 0xffff0000, v15
	v_and_b32_e32 v3, 0xffff0000, v8
	v_lshlrev_b32_e32 v8, 16, v9
	v_and_b32_e32 v9, 0xffff0000, v9
	v_lshlrev_b32_e32 v34, 16, v10
	v_and_b32_e32 v10, 0xffff0000, v10
	v_and_b32_e32 v12, 0xffff0000, v12
	v_lshlrev_b32_e32 v37, 16, v13
	v_and_b32_e32 v13, 0xffff0000, v13
	v_lshlrev_b32_e32 v38, 16, v14
	v_and_b32_e32 v14, 0xffff0000, v14
	v_lshlrev_b32_e32 v40, 16, v16
	v_lshlrev_b32_e32 v41, 16, v20
	v_add_f32_e32 v0, v36, v0
	v_lshlrev_b32_e32 v36, 16, v24
	v_add_f32_e32 v11, v15, v11
	v_and_b32_e32 v15, 0xffff0000, v27
	v_and_b32_e32 v20, 0xffff0000, v20
	v_and_b32_e32 v16, 0xffff0000, v16
	v_lshlrev_b32_e32 v42, 16, v17
	v_lshlrev_b32_e32 v43, 16, v21
	v_and_b32_e32 v21, 0xffff0000, v21
	v_and_b32_e32 v17, 0xffff0000, v17
	v_add_f32_e32 v3, v12, v3
	v_and_b32_e32 v12, 0xffff0000, v24
	v_add_f32_e32 v8, v37, v8
	v_lshlrev_b32_e32 v24, 16, v25
	v_add_f32_e32 v9, v13, v9
	v_and_b32_e32 v13, 0xffff0000, v25
	v_add_f32_e32 v25, v38, v34
	v_lshlrev_b32_e32 v34, 16, v26
	v_add_f32_e32 v10, v14, v10
	v_and_b32_e32 v14, 0xffff0000, v26
	v_add_f32_e32 v26, v39, v35
	v_lshlrev_b32_e32 v35, 16, v27
	v_add_f32_e32 v27, v41, v40
	v_add_f32_e32 v0, v0, v36
	v_add_f32_e32 v11, v11, v15
	v_lshlrev_b32_e32 v15, 16, v28
	v_add_f32_e32 v16, v20, v16
	v_add_f32_e32 v17, v21, v17
	v_add_f32_e32 v3, v3, v12
	v_add_f32_e32 v12, v8, v24
	v_add_f32_e32 v9, v9, v13
	v_add_f32_e32 v13, v25, v34
	v_add_f32_e32 v10, v10, v14
	v_and_b32_e32 v21, 0xffff0000, v28
	v_and_b32_e32 v25, 0xffff0000, v29
	v_cvt_pk_bf16_f32 v8, v0, v3
	v_add_f32_e32 v0, v27, v15
	v_add_f32_e32 v20, v43, v42
	v_add_f32_e32 v14, v26, v35
	v_lshlrev_b32_e32 v24, 16, v29
	v_cvt_pk_bf16_f32 v9, v12, v9
	v_cvt_pk_bf16_f32 v10, v13, v10
	v_cvt_pk_bf16_f32 v11, v14, v11
	v_add_f32_e32 v3, v16, v21
	global_store_dwordx4 v[32:33], v[8:11], off
	v_add_f32_e32 v12, v20, v24
	s_nop 0
	v_cvt_pk_bf16_f32 v8, v0, v3
	v_add_f32_e32 v0, v17, v25
	v_cvt_pk_bf16_f32 v9, v12, v0
	v_lshlrev_b32_e32 v0, 16, v18
	v_lshlrev_b32_e32 v3, 16, v22
	v_add_f32_e32 v0, v3, v0
	v_lshlrev_b32_e32 v3, 16, v30
	v_add_f32_e32 v0, v0, v3
	v_and_b32_e32 v3, 0xffff0000, v22
	v_and_b32_e32 v10, 0xffff0000, v18
	v_add_f32_e32 v3, v3, v10
	v_and_b32_e32 v10, 0xffff0000, v30
	v_add_f32_e32 v3, v3, v10
	v_cvt_pk_bf16_f32 v10, v0, v3
	v_lshlrev_b32_e32 v0, 16, v19
	v_lshlrev_b32_e32 v3, 16, v23
	v_add_f32_e32 v0, v3, v0
	v_lshlrev_b32_e32 v3, 16, v31
	v_add_f32_e32 v0, v0, v3
	v_and_b32_e32 v3, 0xffff0000, v23
	v_and_b32_e32 v11, 0xffff0000, v19
	v_add_f32_e32 v3, v3, v11
	v_and_b32_e32 v11, 0xffff0000, v31
	v_add_f32_e32 v3, v3, v11
	v_cvt_pk_bf16_f32 v11, v0, v3
	global_store_dwordx4 v[32:33], v[8:11], off offset:1024
	s_nop 0
	v_lshl_add_u32 v2, s2, 3, v2
	v_cmp_le_i32_e32 vcc, s9, v2
	s_or_b64 s[16:17], vcc, s[16:17]
	s_andn2_b64 exec, exec, s[16:17]
	s_cbranch_execnz .LBB0_119
.LBB0_120:
	s_waitcnt vmcnt(0)
	s_or_b64 exec, exec, s[14:15]
	s_mov_b64 s[4:5], 0
